# v3 + scan kT prefetch + norm1/norm2 row loops: all 12 modulation/gain loads issued up front, single wait
# baseline (speedup 1.0000x reference)
_Z9mk_kernel6Paramsii:
	s_mov_b32 s100, 0
	s_load_dwordx8 s[52:59], s[0:1], 0x100
	s_load_dwordx2 s[96:97], s[0:1], 0x120
	s_add_u32 s4, s0, 0x120
	s_addc_u32 s5, s1, 0
	v_writelane_b32 v250, s2, 0
	s_waitcnt lgkmcnt(0)
	s_cmpk_gt_i32 s59, 0x3e8
	s_cbranch_scc1 .LBB0_2
	v_and_b32_e32 v168, 0x3ff, v0
	s_load_dword s24, s[0:1], 0x128
	s_cbranch_execz .LBB0_3
	s_branch .LBB0_14

.Lbar_again:
	s_waitcnt vmcnt(0)
	v_readlane_b32 s0, v250, 49
	v_readlane_b32 s1, v250, 50
	s_waitcnt lgkmcnt(0)
	s_barrier
	s_and_saveexec_b64 s[54:55], s[0:1]
	v_readlane_b32 s0, v250, 53
	v_readlane_b32 s1, v250, 54
	s_cbranch_execz .LBB0_79
	s_waitcnt vmcnt(0) expcnt(0) lgkmcnt(0)
	ds_read_b32 v3, v170
	ds_read_b32 v0, v171
	s_waitcnt lgkmcnt(1)
	v_cmp_ne_u32_e32 vcc, 0, v3
	s_cbranch_vccnz .LBB0_43
	s_mov_b32 s20, 1
	s_branch .LBB0_29

.LBB0_79:
	s_or_b64 exec, exec, s[54:55]
	v_readlane_b32 s0, v254, 46
	s_waitcnt lgkmcnt(0)
	s_barrier
	v_readlane_b32 s1, v254, 47
	s_xor_b32 s100, s100, 1
	s_cmp_eq_u32 s100, 1
	s_cbranch_scc1 .Lbar_again

.LBB0_133:
	s_or_b64 exec, exec, s[42:43]
	s_and_b64 s[2:3], exec, vcc
	s_or_b64 s[38:39], s[2:3], s[38:39]
	v_add_u32_e32 v43, 0x1000, v41
	v_lshrrev_b32_e32 v41, 11, v41
	s_movk_i32 s2, 0xfff
	v_add_u32_e32 v41, 1, v41
	v_cmp_lt_i32_e32 vcc, s2, v43
	v_readlane_b32 s2, v254, 61
	v_readlane_b32 s3, v254, 62
	v_cndmask_b32_e32 v41, 0, v41, vcc
	s_mul_i32 s2, s2, 5
	v_add_u32_e32 v41, s2, v41
	v_readlane_b32 s2, v252, 36
	v_readlane_b32 s3, v252, 37
	v_mul_f32_e32 v45, v33, v33
	v_mov_b64_e32 v[50:51], s[2:3]
	v_mad_i64_i32 v[52:53], s[2:3], v41, s97, v[50:51]
	s_mov_b64 s[2:3], 0x1000
	s_nop 0
	v_lshl_add_u64 v[50:51], v[52:53], 0, s[2:3]
	v_mov_b32_e32 v41, v2
	v_lshl_add_u64 v[52:53], v[52:53], 0, v[40:41]
	v_lshl_add_u64 v[68:69], v[50:51], 0, v[40:41]
	v_mul_f32_e32 v47, v29, v29
	global_load_dwordx4 v[100:103], v[0:1], off
	global_load_dwordx4 v[104:107], v[0:1], off offset:1024
	global_load_dwordx4 v[108:111], v[0:1], off offset:2048
	global_load_dwordx4 v[112:115], v[0:1], off offset:3072
	global_load_dwordx4 v[116:119], v[52:53], off
	global_load_dwordx4 v[120:123], v[52:53], off offset:1024
	global_load_dwordx4 v[124:127], v[52:53], off offset:2048
	global_load_dwordx4 v[128:131], v[52:53], off offset:3072
	global_load_dwordx4 v[132:135], v[68:69], off
	global_load_dwordx4 v[136:139], v[68:69], off offset:1024
	global_load_dwordx4 v[140:143], v[68:69], off offset:2048
	global_load_dwordx4 v[144:147], v[68:69], off offset:3072
	v_fmac_f32_e32 v45, v32, v32
	v_fmac_f32_e32 v47, v28, v28
	v_fmac_f32_e32 v45, v34, v34
	v_fmac_f32_e32 v47, v30, v30
	v_fmac_f32_e32 v45, v35, v35
	v_fmac_f32_e32 v47, v31, v31
	v_add_f32_e32 v45, v45, v47
	v_mul_f32_e32 v47, v25, v25
	v_fmac_f32_e32 v47, v24, v24
	v_fmac_f32_e32 v47, v26, v26
	v_fmac_f32_e32 v47, v27, v27
	v_add_f32_e32 v45, v47, v45
	v_mul_f32_e32 v47, v5, v5
	v_fmac_f32_e32 v47, v4, v4
	v_fmac_f32_e32 v47, v6, v6
	v_fmac_f32_e32 v47, v7, v7
	v_add_f32_e32 v45, v47, v45
	ds_bpermute_b32 v47, v3, v45
	v_mov_b32_e32 v43, v2
	v_readlane_b32 s2, v254, 11
	v_readlane_b32 s3, v254, 12
	v_mov_b32_e32 v41, v58
	s_waitcnt lgkmcnt(0)
	v_add_f32_e32 v45, v45, v47
	ds_bpermute_b32 v47, v49, v45
	s_waitcnt lgkmcnt(0)
	v_add_f32_e32 v45, v45, v47
	ds_bpermute_b32 v47, v54, v45
	s_waitcnt lgkmcnt(0)
	v_add_f32_e32 v45, v45, v47
	ds_bpermute_b32 v47, v55, v45
	s_waitcnt lgkmcnt(0)
	v_add_f32_e32 v45, v45, v47
	ds_bpermute_b32 v47, v56, v45
	s_waitcnt lgkmcnt(0)
	v_add_f32_e32 v45, v45, v47
	ds_bpermute_b32 v47, v57, v45
	s_waitcnt lgkmcnt(0)
	v_add_f32_e32 v45, v45, v47
	v_fmamk_f32 v45, v45, 0x3a800000, v174
	v_rsq_f32_e32 v48, v45
	v_mov_b32_e32 v45, v2
	v_mov_b32_e32 v47, v2
	v_pk_mul_f32 v[34:35], v[34:35], v[48:49] op_sel_hi:[1,0]
	v_pk_mul_f32 v[32:33], v[32:33], v[48:49] op_sel_hi:[1,0]
	v_pk_mul_f32 v[30:31], v[30:31], v[48:49] op_sel_hi:[1,0]
	v_pk_mul_f32 v[28:29], v[28:29], v[48:49] op_sel_hi:[1,0]
	v_pk_mul_f32 v[26:27], v[26:27], v[48:49] op_sel_hi:[1,0]
	v_pk_mul_f32 v[24:25], v[24:25], v[48:49] op_sel_hi:[1,0]
	v_pk_mul_f32 v[6:7], v[6:7], v[48:49] op_sel_hi:[1,0]
	v_pk_mul_f32 v[4:5], v[4:5], v[48:49] op_sel_hi:[1,0]
	s_waitcnt vmcnt(0)
	v_pk_mul_f32 v[32:33], v[100:101], v[32:33]
	v_pk_mul_f32 v[34:35], v[102:103], v[34:35]
	v_pk_add_f32 v[60:61], v[134:135], 1.0 op_sel_hi:[1,0]
	v_pk_add_f32 v[62:63], v[132:133], 1.0 op_sel_hi:[1,0]
	v_pk_fma_f32 v[34:35], v[60:61], v[34:35], v[118:119]
	v_pk_fma_f32 v[32:33], v[62:63], v[32:33], v[116:117]
	v_cvt_pk_bf16_f32 v32, v32, v33
	v_cvt_pk_bf16_f32 v33, v34, v35
	global_store_dwordx2 v[36:37], v[32:33], off
	v_pk_mul_f32 v[28:29], v[104:105], v[28:29]
	v_pk_mul_f32 v[30:31], v[106:107], v[30:31]
	v_pk_add_f32 v[60:61], v[138:139], 1.0 op_sel_hi:[1,0]
	v_pk_add_f32 v[62:63], v[136:137], 1.0 op_sel_hi:[1,0]
	v_pk_fma_f32 v[30:31], v[60:61], v[30:31], v[122:123]
	v_pk_fma_f32 v[28:29], v[62:63], v[28:29], v[120:121]
	v_cvt_pk_bf16_f32 v28, v28, v29
	v_cvt_pk_bf16_f32 v29, v30, v31
	global_store_dwordx2 v[36:37], v[28:29], off offset:512
	v_pk_mul_f32 v[24:25], v[108:109], v[24:25]
	v_pk_mul_f32 v[26:27], v[110:111], v[26:27]
	v_pk_add_f32 v[60:61], v[142:143], 1.0 op_sel_hi:[1,0]
	v_pk_add_f32 v[62:63], v[140:141], 1.0 op_sel_hi:[1,0]
	v_pk_fma_f32 v[26:27], v[60:61], v[26:27], v[126:127]
	v_pk_fma_f32 v[24:25], v[62:63], v[24:25], v[124:125]
	v_cvt_pk_bf16_f32 v24, v24, v25
	v_cvt_pk_bf16_f32 v25, v26, v27
	global_store_dwordx2 v[36:37], v[24:25], off offset:1024
	v_pk_mul_f32 v[4:5], v[112:113], v[4:5]
	v_pk_mul_f32 v[6:7], v[114:115], v[6:7]
	v_pk_add_f32 v[60:61], v[146:147], 1.0 op_sel_hi:[1,0]
	v_pk_add_f32 v[62:63], v[144:145], 1.0 op_sel_hi:[1,0]
	v_pk_fma_f32 v[6:7], v[60:61], v[6:7], v[130:131]
	v_pk_fma_f32 v[4:5], v[62:63], v[4:5], v[128:129]
	v_cvt_pk_bf16_f32 v4, v4, v5
	v_cvt_pk_bf16_f32 v5, v6, v7
	global_store_dwordx2 v[36:37], v[4:5], off offset:1536
	v_mov_b32_e32 v32, v12
	v_lshl_add_u64 v[36:37], v[36:37], 0, s[2:3]
	v_readlane_b32 s2, v254, 9
	v_readlane_b32 s3, v254, 10
	v_mov_b32_e32 v33, v13
	v_mov_b32_e32 v34, v14
	v_lshl_add_u64 v[38:39], v[38:39], 0, s[2:3]
	v_mov_b32_e32 v35, v15
	v_mov_b32_e32 v28, v16
	v_mov_b32_e32 v29, v17
	v_mov_b32_e32 v30, v18
	v_mov_b32_e32 v31, v19
	v_mov_b32_e32 v24, v20
	v_mov_b32_e32 v25, v21
	v_mov_b32_e32 v26, v22
	v_mov_b32_e32 v27, v23
	v_mov_b32_e32 v4, v8
	v_mov_b32_e32 v5, v9
	v_mov_b32_e32 v6, v10
	v_mov_b32_e32 v7, v11
	s_andn2_b64 exec, exec, s[38:39]
	s_cbranch_execz .LBB0_136

.LBB0_179:
	s_or_b64 exec, exec, s[42:43]
	s_and_b64 s[2:3], exec, vcc
	s_or_b64 s[40:41], s[2:3], s[40:41]
	v_add_u32_e32 v43, 0x1000, v41
	v_lshrrev_b32_e32 v41, 11, v41
	s_movk_i32 s2, 0xfff
	v_add_u32_e32 v41, 1, v41
	v_cmp_lt_i32_e32 vcc, s2, v43
	v_readlane_b32 s2, v254, 61
	v_readlane_b32 s3, v254, 62
	v_cndmask_b32_e32 v41, 0, v41, vcc
	s_mul_i32 s2, s2, 5
	v_add_u32_e32 v41, s2, v41
	v_readlane_b32 s2, v251, 63
	v_readlane_b32 s3, v252, 0
	v_mul_f32_e32 v45, v33, v33
	v_mov_b64_e32 v[50:51], s[2:3]
	v_mad_i64_i32 v[52:53], s[2:3], v41, s97, v[50:51]
	s_mov_b64 s[2:3], 0x1000
	s_nop 0
	v_lshl_add_u64 v[50:51], v[52:53], 0, s[2:3]
	v_mov_b32_e32 v41, v2
	v_lshl_add_u64 v[52:53], v[52:53], 0, v[40:41]
	v_lshl_add_u64 v[68:69], v[50:51], 0, v[40:41]
	v_mul_f32_e32 v47, v29, v29
	global_load_dwordx4 v[100:103], v[0:1], off
	global_load_dwordx4 v[104:107], v[0:1], off offset:1024
	global_load_dwordx4 v[108:111], v[0:1], off offset:2048
	global_load_dwordx4 v[112:115], v[0:1], off offset:3072
	global_load_dwordx4 v[116:119], v[52:53], off
	global_load_dwordx4 v[120:123], v[52:53], off offset:1024
	global_load_dwordx4 v[124:127], v[52:53], off offset:2048
	global_load_dwordx4 v[128:131], v[52:53], off offset:3072
	global_load_dwordx4 v[132:135], v[68:69], off
	global_load_dwordx4 v[136:139], v[68:69], off offset:1024
	global_load_dwordx4 v[140:143], v[68:69], off offset:2048
	global_load_dwordx4 v[144:147], v[68:69], off offset:3072
	v_fmac_f32_e32 v45, v32, v32
	v_fmac_f32_e32 v47, v28, v28
	v_fmac_f32_e32 v45, v34, v34
	v_fmac_f32_e32 v47, v30, v30
	v_fmac_f32_e32 v45, v35, v35
	v_fmac_f32_e32 v47, v31, v31
	v_add_f32_e32 v45, v45, v47
	v_mul_f32_e32 v47, v25, v25
	v_fmac_f32_e32 v47, v24, v24
	v_fmac_f32_e32 v47, v26, v26
	v_fmac_f32_e32 v47, v27, v27
	v_add_f32_e32 v45, v47, v45
	v_mul_f32_e32 v47, v5, v5
	v_fmac_f32_e32 v47, v4, v4
	v_fmac_f32_e32 v47, v6, v6
	v_fmac_f32_e32 v47, v7, v7
	v_add_f32_e32 v45, v47, v45
	ds_bpermute_b32 v47, v3, v45
	v_mov_b32_e32 v43, v2
	v_readlane_b32 s2, v254, 11
	v_readlane_b32 s3, v254, 12
	v_mov_b32_e32 v41, v58
	s_waitcnt lgkmcnt(0)
	v_add_f32_e32 v45, v45, v47
	ds_bpermute_b32 v47, v49, v45
	s_waitcnt lgkmcnt(0)
	v_add_f32_e32 v45, v45, v47
	ds_bpermute_b32 v47, v54, v45
	s_waitcnt lgkmcnt(0)
	v_add_f32_e32 v45, v45, v47
	ds_bpermute_b32 v47, v55, v45
	s_waitcnt lgkmcnt(0)
	v_add_f32_e32 v45, v45, v47
	ds_bpermute_b32 v47, v56, v45
	s_waitcnt lgkmcnt(0)
	v_add_f32_e32 v45, v45, v47
	ds_bpermute_b32 v47, v57, v45
	s_waitcnt lgkmcnt(0)
	v_add_f32_e32 v45, v45, v47
	v_fmamk_f32 v45, v45, 0x3a800000, v174
	v_rsq_f32_e32 v48, v45
	v_mov_b32_e32 v45, v2
	v_mov_b32_e32 v47, v2
	v_pk_mul_f32 v[34:35], v[34:35], v[48:49] op_sel_hi:[1,0]
	v_pk_mul_f32 v[32:33], v[32:33], v[48:49] op_sel_hi:[1,0]
	v_pk_mul_f32 v[30:31], v[30:31], v[48:49] op_sel_hi:[1,0]
	v_pk_mul_f32 v[28:29], v[28:29], v[48:49] op_sel_hi:[1,0]
	v_pk_mul_f32 v[26:27], v[26:27], v[48:49] op_sel_hi:[1,0]
	v_pk_mul_f32 v[24:25], v[24:25], v[48:49] op_sel_hi:[1,0]
	v_pk_mul_f32 v[6:7], v[6:7], v[48:49] op_sel_hi:[1,0]
	v_pk_mul_f32 v[4:5], v[4:5], v[48:49] op_sel_hi:[1,0]
	s_waitcnt vmcnt(0)
	v_pk_mul_f32 v[32:33], v[100:101], v[32:33]
	v_pk_mul_f32 v[34:35], v[102:103], v[34:35]
	v_pk_add_f32 v[60:61], v[134:135], 1.0 op_sel_hi:[1,0]
	v_pk_add_f32 v[62:63], v[132:133], 1.0 op_sel_hi:[1,0]
	v_pk_fma_f32 v[34:35], v[60:61], v[34:35], v[118:119]
	v_pk_fma_f32 v[32:33], v[62:63], v[32:33], v[116:117]
	v_cvt_pk_bf16_f32 v32, v32, v33
	v_cvt_pk_bf16_f32 v33, v34, v35
	global_store_dwordx2 v[36:37], v[32:33], off
	v_pk_mul_f32 v[28:29], v[104:105], v[28:29]
	v_pk_mul_f32 v[30:31], v[106:107], v[30:31]
	v_pk_add_f32 v[60:61], v[138:139], 1.0 op_sel_hi:[1,0]
	v_pk_add_f32 v[62:63], v[136:137], 1.0 op_sel_hi:[1,0]
	v_pk_fma_f32 v[30:31], v[60:61], v[30:31], v[122:123]
	v_pk_fma_f32 v[28:29], v[62:63], v[28:29], v[120:121]
	v_cvt_pk_bf16_f32 v28, v28, v29
	v_cvt_pk_bf16_f32 v29, v30, v31
	global_store_dwordx2 v[36:37], v[28:29], off offset:512
	v_pk_mul_f32 v[24:25], v[108:109], v[24:25]
	v_pk_mul_f32 v[26:27], v[110:111], v[26:27]
	v_pk_add_f32 v[60:61], v[142:143], 1.0 op_sel_hi:[1,0]
	v_pk_add_f32 v[62:63], v[140:141], 1.0 op_sel_hi:[1,0]
	v_pk_fma_f32 v[26:27], v[60:61], v[26:27], v[126:127]
	v_pk_fma_f32 v[24:25], v[62:63], v[24:25], v[124:125]
	v_cvt_pk_bf16_f32 v24, v24, v25
	v_cvt_pk_bf16_f32 v25, v26, v27
	global_store_dwordx2 v[36:37], v[24:25], off offset:1024
	v_pk_mul_f32 v[4:5], v[112:113], v[4:5]
	v_pk_mul_f32 v[6:7], v[114:115], v[6:7]
	v_pk_add_f32 v[60:61], v[146:147], 1.0 op_sel_hi:[1,0]
	v_pk_add_f32 v[62:63], v[144:145], 1.0 op_sel_hi:[1,0]
	v_pk_fma_f32 v[6:7], v[60:61], v[6:7], v[130:131]
	v_pk_fma_f32 v[4:5], v[62:63], v[4:5], v[128:129]
	v_cvt_pk_bf16_f32 v4, v4, v5
	v_cvt_pk_bf16_f32 v5, v6, v7
	global_store_dwordx2 v[36:37], v[4:5], off offset:1536
	v_mov_b32_e32 v32, v12
	v_lshl_add_u64 v[36:37], v[36:37], 0, s[2:3]
	v_readlane_b32 s2, v254, 9
	v_readlane_b32 s3, v254, 10
	v_mov_b32_e32 v33, v13
	v_mov_b32_e32 v34, v14
	v_lshl_add_u64 v[38:39], v[38:39], 0, s[2:3]
	v_mov_b32_e32 v35, v15
	v_mov_b32_e32 v28, v16
	v_mov_b32_e32 v29, v17
	v_mov_b32_e32 v30, v18
	v_mov_b32_e32 v31, v19
	v_mov_b32_e32 v24, v20
	v_mov_b32_e32 v25, v21
	v_mov_b32_e32 v26, v22
	v_mov_b32_e32 v27, v23
	v_mov_b32_e32 v4, v8
	v_mov_b32_e32 v5, v9
	v_mov_b32_e32 v6, v10
	v_mov_b32_e32 v7, v11
	s_andn2_b64 exec, exec, s[40:41]
	s_cbranch_execz .LBB0_182

	.amdhsa_kernel _Z9mk_kernel6Paramsii
		.amdhsa_group_segment_fixed_size 73760
		.amdhsa_private_segment_fixed_size 0
		.amdhsa_kernarg_size 544
		.amdhsa_user_sgpr_count 2
		.amdhsa_user_sgpr_dispatch_ptr 0
		.amdhsa_user_sgpr_queue_ptr 0
		.amdhsa_user_sgpr_kernarg_segment_ptr 1
		.amdhsa_user_sgpr_dispatch_id 0
		.amdhsa_user_sgpr_kernarg_preload_length 0
		.amdhsa_user_sgpr_kernarg_preload_offset 0
		.amdhsa_user_sgpr_private_segment_size 0
		.amdhsa_uses_dynamic_stack 0
		.amdhsa_enable_private_segment 0
		.amdhsa_system_sgpr_workgroup_id_x 1
		.amdhsa_system_sgpr_workgroup_id_y 0
		.amdhsa_system_sgpr_workgroup_id_z 0
		.amdhsa_system_sgpr_workgroup_info 0
		.amdhsa_system_vgpr_workitem_id 2
		.amdhsa_next_free_vgpr 256
		.amdhsa_next_free_sgpr 102
		.amdhsa_accum_offset 256
		.amdhsa_reserve_vcc 1
		.amdhsa_float_round_mode_32 0
		.amdhsa_float_round_mode_16_64 0
		.amdhsa_float_denorm_mode_32 3
		.amdhsa_float_denorm_mode_16_64 3
		.amdhsa_dx10_clamp 1
		.amdhsa_ieee_mode 1
		.amdhsa_fp16_overflow 0
		.amdhsa_tg_split 0
		.amdhsa_exception_fp_ieee_invalid_op 0
		.amdhsa_exception_fp_denorm_src 0
		.amdhsa_exception_fp_ieee_div_zero 0
		.amdhsa_exception_fp_ieee_overflow 0
		.amdhsa_exception_fp_ieee_underflow 0
		.amdhsa_exception_fp_ieee_inexact 0
		.amdhsa_exception_int_div_zero 0
	.end_amdhsa_kernel

.Lfunc_end0:
	.size	_Z9mk_kernel6Paramsii, .Lfunc_end0-_Z9mk_kernel6Paramsii
	.set _Z9mk_kernel6Paramsii.num_vgpr, 256
	.set _Z9mk_kernel6Paramsii.num_agpr, 0
	.set _Z9mk_kernel6Paramsii.numbered_sgpr, 102
	.set _Z9mk_kernel6Paramsii.num_named_barrier, 0
	.set _Z9mk_kernel6Paramsii.private_seg_size, 0
	.set _Z9mk_kernel6Paramsii.uses_vcc, 1
	.set _Z9mk_kernel6Paramsii.uses_flat_scratch, 0
	.set _Z9mk_kernel6Paramsii.has_dyn_sized_stack, 0
	.set _Z9mk_kernel6Paramsii.has_recursion, 0
	.set _Z9mk_kernel6Paramsii.has_indirect_call, 0

amdhsa.kernels:
  - .agpr_count:     0
    .args:
      - .offset:         0
        .size:           280
        .value_kind:     by_value
      - .offset:         280
        .size:           4
        .value_kind:     by_value
      - .offset:         284
        .size:           4
        .value_kind:     by_value
      - .offset:         288
        .size:           4
        .value_kind:     hidden_block_count_x
      - .offset:         292
        .size:           4
        .value_kind:     hidden_block_count_y
      - .offset:         296
        .size:           4
        .value_kind:     hidden_block_count_z
      - .offset:         300
        .size:           2
        .value_kind:     hidden_group_size_x
      - .offset:         302
        .size:           2
        .value_kind:     hidden_group_size_y
      - .offset:         304
        .size:           2
        .value_kind:     hidden_group_size_z
      - .offset:         306
        .size:           2
        .value_kind:     hidden_remainder_x
      - .offset:         308
        .size:           2
        .value_kind:     hidden_remainder_y
      - .offset:         310
        .size:           2
        .value_kind:     hidden_remainder_z
      - .offset:         328
        .size:           8
        .value_kind:     hidden_global_offset_x
      - .offset:         336
        .size:           8
        .value_kind:     hidden_global_offset_y
      - .offset:         344
        .size:           8
        .value_kind:     hidden_global_offset_z
      - .offset:         352
        .size:           2
        .value_kind:     hidden_grid_dims
      - .offset:         376
        .size:           8
        .value_kind:     hidden_multigrid_sync_arg
    .group_segment_fixed_size: 73760
    .kernarg_segment_align: 8
    .kernarg_segment_size: 544
    .language:       OpenCL C
    .language_version:
      - 2
      - 0
    .max_flat_workgroup_size: 256
    .name:           _Z9mk_kernel6Paramsii
    .private_segment_fixed_size: 0
    .sgpr_count:     108
    .sgpr_spill_count: 336
    .symbol:         _Z9mk_kernel6Paramsii.kd
    .uniform_work_group_size: 1
    .uses_dynamic_stack: false
    .vgpr_count:     256
    .vgpr_spill_count: 0
    .wavefront_size: 64
